# Static priority raise for the OTHER half: s_setprio 1 for waves 0-3 around each GEMM K-loop
# speedup vs baseline: 1.0082x; 1.0001x over previous
.LBB0_162:
	s_ashr_i32 s19, s18, 31
	s_lshl_b64 s[20:21], s[18:19], 19
	s_add_u32 s20, s8, s20
	s_addc_u32 s21, s9, s21
	s_and_b64 s[22:23], s[4:5], exec
	s_cselect_b32 s19, s21, s27
	s_cselect_b32 s51, s20, s26
	s_ashr_i32 s17, s16, 31
	s_lshl_b64 s[22:23], s[16:17], 19
	s_add_u32 s22, s31, s22
	s_addc_u32 s23, s34, s23
	s_and_b64 s[28:29], s[4:5], exec
	s_cselect_b32 s17, s23, s25
	s_cselect_b32 s52, s22, s24
	s_add_u32 s53, s24, 0x100
	s_addc_u32 s54, s25, 0
	s_add_u32 s24, s26, 0x40080
	v_mov_b32_e32 v0, 0
	s_addc_u32 s25, s27, 0
	s_mov_b32 s55, -2
	v_mov_b32_e32 v1, v0
	v_mov_b32_e32 v2, v0
	v_mov_b32_e32 v3, v0
	v_mov_b32_e32 v4, v0
	v_mov_b32_e32 v5, v0
	v_mov_b32_e32 v6, v0
	v_mov_b32_e32 v7, v0
	v_mov_b32_e32 v16, v0
	v_mov_b32_e32 v17, v0
	s_waitcnt vmcnt(0)
	v_mov_b32_e32 v18, v0
	v_mov_b32_e32 v19, v0
	v_mov_b32_e32 v20, v0
	v_mov_b32_e32 v21, v0
	v_mov_b32_e32 v22, v0
	v_mov_b32_e32 v23, v0
	v_mov_b32_e32 v32, v0
	v_mov_b32_e32 v33, v0
	v_mov_b32_e32 v34, v0
	v_mov_b32_e32 v35, v0
	v_mov_b32_e32 v36, v0
	v_mov_b32_e32 v37, v0
	v_mov_b32_e32 v38, v0
	v_mov_b32_e32 v39, v0
	v_mov_b32_e32 v48, v0
	v_mov_b32_e32 v49, v0
	v_mov_b32_e32 v50, v0
	v_mov_b32_e32 v51, v0
	v_mov_b32_e32 v52, v0
	v_mov_b32_e32 v53, v0
	v_mov_b32_e32 v54, v0
	v_mov_b32_e32 v55, v0
	v_mov_b32_e32 v8, v0
	v_mov_b32_e32 v9, v0
	v_mov_b32_e32 v10, v0
	v_mov_b32_e32 v11, v0
	v_mov_b32_e32 v12, v0
	v_mov_b32_e32 v13, v0
	v_mov_b32_e32 v14, v0
	v_mov_b32_e32 v15, v0
	v_mov_b32_e32 v24, v0
	v_mov_b32_e32 v25, v0
	v_mov_b32_e32 v26, v0
	v_mov_b32_e32 v27, v0
	v_mov_b32_e32 v28, v0
	v_mov_b32_e32 v29, v0
	v_mov_b32_e32 v30, v0
	v_mov_b32_e32 v31, v0
	v_mov_b32_e32 v40, v0
	v_mov_b32_e32 v41, v0
	v_mov_b32_e32 v42, v0
	v_mov_b32_e32 v43, v0
	v_mov_b32_e32 v44, v0
	v_mov_b32_e32 v45, v0
	v_mov_b32_e32 v46, v0
	v_mov_b32_e32 v47, v0
	v_mov_b32_e32 v56, v0
	v_mov_b32_e32 v57, v0
	v_mov_b32_e32 v58, v0
	v_mov_b32_e32 v59, v0
	v_mov_b32_e32 v60, v0
	v_mov_b32_e32 v61, v0
	v_mov_b32_e32 v62, v0
	v_mov_b32_e32 v63, v0
	v_mov_b32_e32 v64, v0
	v_mov_b32_e32 v65, v0
	v_mov_b32_e32 v66, v0
	v_mov_b32_e32 v67, v0
	v_mov_b32_e32 v68, v0
	v_mov_b32_e32 v69, v0
	v_mov_b32_e32 v70, v0
	v_mov_b32_e32 v71, v0
	v_mov_b32_e32 v80, v0
	v_mov_b32_e32 v81, v0
	v_mov_b32_e32 v82, v0
	v_mov_b32_e32 v83, v0
	v_mov_b32_e32 v84, v0
	v_mov_b32_e32 v85, v0
	v_mov_b32_e32 v86, v0
	v_mov_b32_e32 v87, v0
	v_mov_b32_e32 v96, v0
	v_mov_b32_e32 v97, v0
	v_mov_b32_e32 v98, v0
	v_mov_b32_e32 v99, v0
	v_mov_b32_e32 v100, v0
	v_mov_b32_e32 v101, v0
	v_mov_b32_e32 v102, v0
	v_mov_b32_e32 v103, v0
	v_mov_b32_e32 v112, v0
	v_mov_b32_e32 v113, v0
	v_mov_b32_e32 v114, v0
	v_mov_b32_e32 v115, v0
	v_mov_b32_e32 v116, v0
	v_mov_b32_e32 v117, v0
	v_mov_b32_e32 v118, v0
	v_mov_b32_e32 v119, v0
	v_mov_b32_e32 v72, v0
	v_mov_b32_e32 v73, v0
	v_mov_b32_e32 v74, v0
	v_mov_b32_e32 v75, v0
	v_mov_b32_e32 v76, v0
	v_mov_b32_e32 v77, v0
	v_mov_b32_e32 v78, v0
	v_mov_b32_e32 v79, v0
	v_mov_b32_e32 v88, v0
	v_mov_b32_e32 v89, v0
	v_mov_b32_e32 v90, v0
	v_mov_b32_e32 v91, v0
	v_mov_b32_e32 v92, v0
	v_mov_b32_e32 v93, v0
	v_mov_b32_e32 v94, v0
	v_mov_b32_e32 v95, v0
	v_mov_b32_e32 v104, v0
	v_mov_b32_e32 v105, v0
	v_mov_b32_e32 v106, v0
	v_mov_b32_e32 v107, v0
	v_mov_b32_e32 v108, v0
	v_mov_b32_e32 v109, v0
	v_mov_b32_e32 v110, v0
	v_mov_b32_e32 v111, v0
	v_mov_b32_e32 v120, v0
	v_mov_b32_e32 v121, v0
	v_mov_b32_e32 v122, v0
	v_mov_b32_e32 v123, v0
	v_mov_b32_e32 v124, v0
	v_mov_b32_e32 v125, v0
	v_mov_b32_e32 v126, v0
	v_mov_b32_e32 v127, v0
	v_add_u32_e32 v204, 0x80, v128
	v_add_u32_e32 v205, 0x80, v130
	v_add_u32_e32 v220, 0x80, v132
	v_add_u32_e32 v221, 0x80, v134
	v_readfirstlane_b32 s101, v206
	s_nop 3
	s_lshr_b32 s101, s101, 8
	s_cmp_eq_u32 s101, 0
	s_cbranch_scc0 .Lprio_skip_21
	s_setprio 1

.LBB0_605:
	s_ashr_i32 s21, s20, 31
	s_lshl_b64 s[22:23], s[20:21], 19
	s_add_u32 s22, s39, s22
	s_addc_u32 s23, s40, s23
	s_and_b64 s[24:25], s[6:7], exec
	s_cselect_b32 s21, s23, s29
	s_cselect_b32 s27, s22, s28
	s_ashr_i32 s19, s18, 31
	s_lshl_b64 s[24:25], s[18:19], 19
	s_add_u32 s24, s41, s24
	s_addc_u32 s25, s42, s25
	s_and_b64 s[34:35], s[6:7], exec
	s_cselect_b32 s19, s25, s31
	s_cselect_b32 s55, s24, s30
	s_add_u32 s56, s30, 0x100
	v_mov_b32_e32 v0, 0
	s_addc_u32 s57, s31, 0
	s_mov_b32 s58, -2
	v_mov_b32_e32 v1, v0
	v_mov_b32_e32 v2, v0
	v_mov_b32_e32 v3, v0
	v_mov_b32_e32 v4, v0
	v_mov_b32_e32 v5, v0
	v_mov_b32_e32 v6, v0
	v_mov_b32_e32 v7, v0
	v_mov_b32_e32 v16, v0
	v_mov_b32_e32 v17, v0
	v_mov_b32_e32 v18, v0
	v_mov_b32_e32 v19, v0
	v_mov_b32_e32 v20, v0
	v_mov_b32_e32 v21, v0
	v_mov_b32_e32 v22, v0
	v_mov_b32_e32 v23, v0
	v_mov_b32_e32 v32, v0
	v_mov_b32_e32 v33, v0
	v_mov_b32_e32 v34, v0
	v_mov_b32_e32 v35, v0
	v_mov_b32_e32 v36, v0
	v_mov_b32_e32 v37, v0
	v_mov_b32_e32 v38, v0
	v_mov_b32_e32 v39, v0
	v_mov_b32_e32 v48, v0
	v_mov_b32_e32 v49, v0
	v_mov_b32_e32 v50, v0
	v_mov_b32_e32 v51, v0
	v_mov_b32_e32 v52, v0
	v_mov_b32_e32 v53, v0
	v_mov_b32_e32 v54, v0
	v_mov_b32_e32 v55, v0
	v_mov_b32_e32 v8, v0
	v_mov_b32_e32 v9, v0
	v_mov_b32_e32 v10, v0
	v_mov_b32_e32 v11, v0
	v_mov_b32_e32 v12, v0
	v_mov_b32_e32 v13, v0
	v_mov_b32_e32 v14, v0
	v_mov_b32_e32 v15, v0
	v_mov_b32_e32 v24, v0
	v_mov_b32_e32 v25, v0
	v_mov_b32_e32 v26, v0
	v_mov_b32_e32 v27, v0
	v_mov_b32_e32 v28, v0
	v_mov_b32_e32 v29, v0
	v_mov_b32_e32 v30, v0
	v_mov_b32_e32 v31, v0
	v_mov_b32_e32 v40, v0
	v_mov_b32_e32 v41, v0
	v_mov_b32_e32 v42, v0
	v_mov_b32_e32 v43, v0
	v_mov_b32_e32 v44, v0
	v_mov_b32_e32 v45, v0
	v_mov_b32_e32 v46, v0
	v_mov_b32_e32 v47, v0
	v_mov_b32_e32 v56, v0
	v_mov_b32_e32 v57, v0
	v_mov_b32_e32 v58, v0
	v_mov_b32_e32 v59, v0
	v_mov_b32_e32 v60, v0
	v_mov_b32_e32 v61, v0
	v_mov_b32_e32 v62, v0
	v_mov_b32_e32 v63, v0
	v_mov_b32_e32 v64, v0
	v_mov_b32_e32 v65, v0
	v_mov_b32_e32 v66, v0
	v_mov_b32_e32 v67, v0
	v_mov_b32_e32 v68, v0
	v_mov_b32_e32 v69, v0
	v_mov_b32_e32 v70, v0
	v_mov_b32_e32 v71, v0
	v_mov_b32_e32 v80, v0
	v_mov_b32_e32 v81, v0
	v_mov_b32_e32 v82, v0
	v_mov_b32_e32 v83, v0
	v_mov_b32_e32 v84, v0
	v_mov_b32_e32 v85, v0
	v_mov_b32_e32 v86, v0
	v_mov_b32_e32 v87, v0
	v_mov_b32_e32 v96, v0
	v_mov_b32_e32 v97, v0
	v_mov_b32_e32 v98, v0
	v_mov_b32_e32 v99, v0
	v_mov_b32_e32 v100, v0
	v_mov_b32_e32 v101, v0
	v_mov_b32_e32 v102, v0
	v_mov_b32_e32 v103, v0
	v_mov_b32_e32 v112, v0
	v_mov_b32_e32 v113, v0
	v_mov_b32_e32 v114, v0
	v_mov_b32_e32 v115, v0
	v_mov_b32_e32 v116, v0
	v_mov_b32_e32 v117, v0
	v_mov_b32_e32 v118, v0
	v_mov_b32_e32 v119, v0
	v_mov_b32_e32 v72, v0
	v_mov_b32_e32 v73, v0
	v_mov_b32_e32 v74, v0
	v_mov_b32_e32 v75, v0
	v_mov_b32_e32 v76, v0
	v_mov_b32_e32 v77, v0
	v_mov_b32_e32 v78, v0
	v_mov_b32_e32 v79, v0
	v_mov_b32_e32 v88, v0
	v_mov_b32_e32 v89, v0
	v_mov_b32_e32 v90, v0
	v_mov_b32_e32 v91, v0
	v_mov_b32_e32 v92, v0
	v_mov_b32_e32 v93, v0
	v_mov_b32_e32 v94, v0
	v_mov_b32_e32 v95, v0
	v_mov_b32_e32 v104, v0
	v_mov_b32_e32 v105, v0
	v_mov_b32_e32 v106, v0
	v_mov_b32_e32 v107, v0
	v_mov_b32_e32 v108, v0
	v_mov_b32_e32 v109, v0
	v_mov_b32_e32 v110, v0
	v_mov_b32_e32 v111, v0
	v_mov_b32_e32 v120, v0
	v_mov_b32_e32 v121, v0
	v_mov_b32_e32 v122, v0
	v_mov_b32_e32 v123, v0
	v_mov_b32_e32 v124, v0
	v_mov_b32_e32 v125, v0
	v_mov_b32_e32 v126, v0
	v_mov_b32_e32 v127, v0
	v_add_u32_e32 v212, 0x80, v128
	v_add_u32_e32 v213, 0x80, v130
	v_readfirstlane_b32 s101, v206
	s_nop 3
	s_lshr_b32 s101, s101, 8
	s_cmp_eq_u32 s101, 0
	s_cbranch_scc0 .Lprio_skip_20
	s_setprio 1

.LBB0_698:
	s_ashr_i32 s21, s20, 31
	s_lshl_b64 s[22:23], s[20:21], 19
	s_add_u32 s22, s8, s22
	s_addc_u32 s23, s9, s23
	s_and_b64 s[24:25], s[4:5], exec
	s_cselect_b32 s21, s23, s29
	s_cselect_b32 s49, s22, s28
	s_ashr_i32 s19, s18, 31
	s_lshl_b64 s[24:25], s[18:19], 19
	s_add_u32 s24, s36, s24
	s_addc_u32 s25, s37, s25
	s_and_b64 s[30:31], s[4:5], exec
	s_cselect_b32 s19, s25, s27
	s_cselect_b32 s50, s24, s26
	s_add_u32 s51, s26, 0x100
	s_addc_u32 s52, s27, 0
	s_add_u32 s26, s28, 0x40080
	v_mov_b32_e32 v0, 0
	s_addc_u32 s27, s29, 0
	s_mov_b32 s53, -2
	v_mov_b32_e32 v1, v0
	v_mov_b32_e32 v2, v0
	v_mov_b32_e32 v3, v0
	v_mov_b32_e32 v4, v0
	v_mov_b32_e32 v5, v0
	v_mov_b32_e32 v6, v0
	v_mov_b32_e32 v7, v0
	v_mov_b32_e32 v16, v0
	v_mov_b32_e32 v17, v0
	v_mov_b32_e32 v18, v0
	v_mov_b32_e32 v19, v0
	v_mov_b32_e32 v20, v0
	v_mov_b32_e32 v21, v0
	v_mov_b32_e32 v22, v0
	v_mov_b32_e32 v23, v0
	v_mov_b32_e32 v32, v0
	v_mov_b32_e32 v33, v0
	v_mov_b32_e32 v34, v0
	v_mov_b32_e32 v35, v0
	v_mov_b32_e32 v36, v0
	v_mov_b32_e32 v37, v0
	v_mov_b32_e32 v38, v0
	v_mov_b32_e32 v39, v0
	v_mov_b32_e32 v48, v0
	v_mov_b32_e32 v49, v0
	v_mov_b32_e32 v50, v0
	v_mov_b32_e32 v51, v0
	v_mov_b32_e32 v52, v0
	v_mov_b32_e32 v53, v0
	v_mov_b32_e32 v54, v0
	v_mov_b32_e32 v55, v0
	v_mov_b32_e32 v8, v0
	v_mov_b32_e32 v9, v0
	v_mov_b32_e32 v10, v0
	v_mov_b32_e32 v11, v0
	v_mov_b32_e32 v12, v0
	v_mov_b32_e32 v13, v0
	v_mov_b32_e32 v14, v0
	v_mov_b32_e32 v15, v0
	v_mov_b32_e32 v24, v0
	v_mov_b32_e32 v25, v0
	v_mov_b32_e32 v26, v0
	v_mov_b32_e32 v27, v0
	v_mov_b32_e32 v28, v0
	v_mov_b32_e32 v29, v0
	v_mov_b32_e32 v30, v0
	v_mov_b32_e32 v31, v0
	v_mov_b32_e32 v40, v0
	v_mov_b32_e32 v41, v0
	v_mov_b32_e32 v42, v0
	v_mov_b32_e32 v43, v0
	v_mov_b32_e32 v44, v0
	v_mov_b32_e32 v45, v0
	v_mov_b32_e32 v46, v0
	v_mov_b32_e32 v47, v0
	v_mov_b32_e32 v56, v0
	v_mov_b32_e32 v57, v0
	v_mov_b32_e32 v58, v0
	v_mov_b32_e32 v59, v0
	v_mov_b32_e32 v60, v0
	v_mov_b32_e32 v61, v0
	v_mov_b32_e32 v62, v0
	v_mov_b32_e32 v63, v0
	v_mov_b32_e32 v64, v0
	v_mov_b32_e32 v65, v0
	v_mov_b32_e32 v66, v0
	v_mov_b32_e32 v67, v0
	v_mov_b32_e32 v68, v0
	v_mov_b32_e32 v69, v0
	v_mov_b32_e32 v70, v0
	v_mov_b32_e32 v71, v0
	v_mov_b32_e32 v80, v0
	v_mov_b32_e32 v81, v0
	v_mov_b32_e32 v82, v0
	v_mov_b32_e32 v83, v0
	v_mov_b32_e32 v84, v0
	v_mov_b32_e32 v85, v0
	v_mov_b32_e32 v86, v0
	v_mov_b32_e32 v87, v0
	v_mov_b32_e32 v96, v0
	v_mov_b32_e32 v97, v0
	v_mov_b32_e32 v98, v0
	v_mov_b32_e32 v99, v0
	v_mov_b32_e32 v100, v0
	v_mov_b32_e32 v101, v0
	v_mov_b32_e32 v102, v0
	v_mov_b32_e32 v103, v0
	v_mov_b32_e32 v112, v0
	v_mov_b32_e32 v113, v0
	v_mov_b32_e32 v114, v0
	v_mov_b32_e32 v115, v0
	v_mov_b32_e32 v116, v0
	v_mov_b32_e32 v117, v0
	v_mov_b32_e32 v118, v0
	v_mov_b32_e32 v119, v0
	v_mov_b32_e32 v72, v0
	v_mov_b32_e32 v73, v0
	v_mov_b32_e32 v74, v0
	v_mov_b32_e32 v75, v0
	v_mov_b32_e32 v76, v0
	v_mov_b32_e32 v77, v0
	v_mov_b32_e32 v78, v0
	v_mov_b32_e32 v79, v0
	v_mov_b32_e32 v88, v0
	v_mov_b32_e32 v89, v0
	v_mov_b32_e32 v90, v0
	v_mov_b32_e32 v91, v0
	v_mov_b32_e32 v92, v0
	v_mov_b32_e32 v93, v0
	v_mov_b32_e32 v94, v0
	v_mov_b32_e32 v95, v0
	v_mov_b32_e32 v104, v0
	v_mov_b32_e32 v105, v0
	v_mov_b32_e32 v106, v0
	v_mov_b32_e32 v107, v0
	v_mov_b32_e32 v108, v0
	v_mov_b32_e32 v109, v0
	v_mov_b32_e32 v110, v0
	v_mov_b32_e32 v111, v0
	v_mov_b32_e32 v120, v0
	v_mov_b32_e32 v121, v0
	v_mov_b32_e32 v122, v0
	v_mov_b32_e32 v123, v0
	v_mov_b32_e32 v124, v0
	v_mov_b32_e32 v125, v0
	v_mov_b32_e32 v126, v0
	v_mov_b32_e32 v127, v0
	v_add_u32_e32 v204, 0x80, v128
	v_add_u32_e32 v205, 0x80, v130
	v_add_u32_e32 v220, 0x80, v132
	v_add_u32_e32 v221, 0x80, v134
	v_readfirstlane_b32 s101, v206
	s_nop 3
	s_lshr_b32 s101, s101, 8
	s_cmp_eq_u32 s101, 0
	s_cbranch_scc0 .Lprio_skip_19
	s_setprio 1

.LBB0_777:
	s_ashr_i32 s21, s20, 31
	s_lshl_b64 s[22:23], s[20:21], 21
	s_add_u32 s22, s39, s22
	s_addc_u32 s23, s40, s23
	s_and_b64 s[24:25], s[6:7], exec
	s_cselect_b32 s21, s23, s29
	s_cselect_b32 s27, s22, s28
	s_ashr_i32 s19, s18, 31
	s_lshl_b64 s[24:25], s[18:19], 21
	s_add_u32 s24, s41, s24
	s_addc_u32 s25, s42, s25
	s_and_b64 s[34:35], s[6:7], exec
	s_cselect_b32 s19, s25, s31
	s_cselect_b32 s55, s24, s30
	s_add_u32 s56, s30, 0x100
	v_mov_b32_e32 v0, 0
	s_addc_u32 s57, s31, 0
	s_mov_b32 s58, -2
	v_mov_b32_e32 v1, v0
	v_mov_b32_e32 v2, v0
	v_mov_b32_e32 v3, v0
	v_mov_b32_e32 v4, v0
	v_mov_b32_e32 v5, v0
	v_mov_b32_e32 v6, v0
	v_mov_b32_e32 v7, v0
	v_mov_b32_e32 v16, v0
	v_mov_b32_e32 v17, v0
	v_mov_b32_e32 v18, v0
	v_mov_b32_e32 v19, v0
	v_mov_b32_e32 v20, v0
	v_mov_b32_e32 v21, v0
	v_mov_b32_e32 v22, v0
	v_mov_b32_e32 v23, v0
	v_mov_b32_e32 v32, v0
	v_mov_b32_e32 v33, v0
	v_mov_b32_e32 v34, v0
	v_mov_b32_e32 v35, v0
	v_mov_b32_e32 v36, v0
	v_mov_b32_e32 v37, v0
	v_mov_b32_e32 v38, v0
	v_mov_b32_e32 v39, v0
	v_mov_b32_e32 v48, v0
	v_mov_b32_e32 v49, v0
	v_mov_b32_e32 v50, v0
	v_mov_b32_e32 v51, v0
	v_mov_b32_e32 v52, v0
	v_mov_b32_e32 v53, v0
	v_mov_b32_e32 v54, v0
	v_mov_b32_e32 v55, v0
	v_mov_b32_e32 v8, v0
	v_mov_b32_e32 v9, v0
	v_mov_b32_e32 v10, v0
	v_mov_b32_e32 v11, v0
	v_mov_b32_e32 v12, v0
	v_mov_b32_e32 v13, v0
	v_mov_b32_e32 v14, v0
	v_mov_b32_e32 v15, v0
	v_mov_b32_e32 v24, v0
	v_mov_b32_e32 v25, v0
	v_mov_b32_e32 v26, v0
	v_mov_b32_e32 v27, v0
	v_mov_b32_e32 v28, v0
	v_mov_b32_e32 v29, v0
	v_mov_b32_e32 v30, v0
	v_mov_b32_e32 v31, v0
	v_mov_b32_e32 v40, v0
	v_mov_b32_e32 v41, v0
	v_mov_b32_e32 v42, v0
	v_mov_b32_e32 v43, v0
	v_mov_b32_e32 v44, v0
	v_mov_b32_e32 v45, v0
	v_mov_b32_e32 v46, v0
	v_mov_b32_e32 v47, v0
	v_mov_b32_e32 v56, v0
	v_mov_b32_e32 v57, v0
	v_mov_b32_e32 v58, v0
	v_mov_b32_e32 v59, v0
	v_mov_b32_e32 v60, v0
	v_mov_b32_e32 v61, v0
	v_mov_b32_e32 v62, v0
	v_mov_b32_e32 v63, v0
	v_mov_b32_e32 v64, v0
	v_mov_b32_e32 v65, v0
	v_mov_b32_e32 v66, v0
	v_mov_b32_e32 v67, v0
	v_mov_b32_e32 v68, v0
	v_mov_b32_e32 v69, v0
	v_mov_b32_e32 v70, v0
	v_mov_b32_e32 v71, v0
	v_mov_b32_e32 v80, v0
	v_mov_b32_e32 v81, v0
	v_mov_b32_e32 v82, v0
	v_mov_b32_e32 v83, v0
	v_mov_b32_e32 v84, v0
	v_mov_b32_e32 v85, v0
	v_mov_b32_e32 v86, v0
	v_mov_b32_e32 v87, v0
	v_mov_b32_e32 v96, v0
	v_mov_b32_e32 v97, v0
	v_mov_b32_e32 v98, v0
	v_mov_b32_e32 v99, v0
	v_mov_b32_e32 v100, v0
	v_mov_b32_e32 v101, v0
	v_mov_b32_e32 v102, v0
	v_mov_b32_e32 v103, v0
	v_mov_b32_e32 v112, v0
	v_mov_b32_e32 v113, v0
	v_mov_b32_e32 v114, v0
	v_mov_b32_e32 v115, v0
	v_mov_b32_e32 v116, v0
	v_mov_b32_e32 v117, v0
	v_mov_b32_e32 v118, v0
	v_mov_b32_e32 v119, v0
	v_mov_b32_e32 v72, v0
	v_mov_b32_e32 v73, v0
	v_mov_b32_e32 v74, v0
	v_mov_b32_e32 v75, v0
	v_mov_b32_e32 v76, v0
	v_mov_b32_e32 v77, v0
	v_mov_b32_e32 v78, v0
	v_mov_b32_e32 v79, v0
	v_mov_b32_e32 v88, v0
	v_mov_b32_e32 v89, v0
	v_mov_b32_e32 v90, v0
	v_mov_b32_e32 v91, v0
	v_mov_b32_e32 v92, v0
	v_mov_b32_e32 v93, v0
	v_mov_b32_e32 v94, v0
	v_mov_b32_e32 v95, v0
	v_mov_b32_e32 v104, v0
	v_mov_b32_e32 v105, v0
	v_mov_b32_e32 v106, v0
	v_mov_b32_e32 v107, v0
	v_mov_b32_e32 v108, v0
	v_mov_b32_e32 v109, v0
	v_mov_b32_e32 v110, v0
	v_mov_b32_e32 v111, v0
	v_mov_b32_e32 v120, v0
	v_mov_b32_e32 v121, v0
	v_mov_b32_e32 v122, v0
	v_mov_b32_e32 v123, v0
	v_mov_b32_e32 v124, v0
	v_mov_b32_e32 v125, v0
	v_mov_b32_e32 v126, v0
	v_mov_b32_e32 v127, v0
	v_add_u32_e32 v212, 0x80, v128
	v_add_u32_e32 v213, 0x80, v130
	v_readfirstlane_b32 s101, v206
	s_nop 3
	s_lshr_b32 s101, s101, 8
	s_cmp_eq_u32 s101, 0
	s_cbranch_scc0 .Lprio_skip_18
	s_setprio 1

.LBB0_894:
	s_ashr_i32 s29, s28, 31
	s_lshl_b64 s[30:31], s[28:29], 19
	s_add_u32 s30, s8, s30
	s_addc_u32 s31, s9, s31
	s_and_b64 s[34:35], s[6:7], exec
	s_cselect_b32 s3, s31, s39
	s_cselect_b32 s29, s30, s38
	s_ashr_i32 s27, s26, 31
	s_lshl_b64 s[34:35], s[26:27], 19
	s_add_u32 s34, s43, s34
	s_addc_u32 s35, s44, s35
	s_and_b64 s[40:41], s[6:7], exec
	s_cselect_b32 s27, s35, s37
	s_cselect_b32 s58, s34, s36
	s_add_u32 s59, s36, 0x100
	s_addc_u32 s60, s37, 0
	s_add_u32 s36, s38, 0x40080
	v_mov_b32_e32 v0, 0
	s_addc_u32 s37, s39, 0
	s_mov_b32 s61, -2
	v_mov_b32_e32 v1, v0
	v_mov_b32_e32 v2, v0
	v_mov_b32_e32 v3, v0
	v_mov_b32_e32 v4, v0
	v_mov_b32_e32 v5, v0
	v_mov_b32_e32 v6, v0
	v_mov_b32_e32 v7, v0
	v_mov_b32_e32 v16, v0
	v_mov_b32_e32 v17, v0
	v_mov_b32_e32 v18, v0
	v_mov_b32_e32 v19, v0
	v_mov_b32_e32 v20, v0
	v_mov_b32_e32 v21, v0
	v_mov_b32_e32 v22, v0
	v_mov_b32_e32 v23, v0
	v_mov_b32_e32 v32, v0
	v_mov_b32_e32 v33, v0
	v_mov_b32_e32 v34, v0
	v_mov_b32_e32 v35, v0
	v_mov_b32_e32 v36, v0
	v_mov_b32_e32 v37, v0
	v_mov_b32_e32 v38, v0
	v_mov_b32_e32 v39, v0
	v_mov_b32_e32 v48, v0
	v_mov_b32_e32 v49, v0
	v_mov_b32_e32 v50, v0
	v_mov_b32_e32 v51, v0
	v_mov_b32_e32 v52, v0
	v_mov_b32_e32 v53, v0
	v_mov_b32_e32 v54, v0
	v_mov_b32_e32 v55, v0
	v_mov_b32_e32 v8, v0
	v_mov_b32_e32 v9, v0
	v_mov_b32_e32 v10, v0
	v_mov_b32_e32 v11, v0
	v_mov_b32_e32 v12, v0
	v_mov_b32_e32 v13, v0
	v_mov_b32_e32 v14, v0
	v_mov_b32_e32 v15, v0
	v_mov_b32_e32 v24, v0
	v_mov_b32_e32 v25, v0
	v_mov_b32_e32 v26, v0
	v_mov_b32_e32 v27, v0
	v_mov_b32_e32 v28, v0
	v_mov_b32_e32 v29, v0
	v_mov_b32_e32 v30, v0
	v_mov_b32_e32 v31, v0
	v_mov_b32_e32 v40, v0
	v_mov_b32_e32 v41, v0
	v_mov_b32_e32 v42, v0
	v_mov_b32_e32 v43, v0
	v_mov_b32_e32 v44, v0
	v_mov_b32_e32 v45, v0
	v_mov_b32_e32 v46, v0
	v_mov_b32_e32 v47, v0
	v_mov_b32_e32 v56, v0
	v_mov_b32_e32 v57, v0
	v_mov_b32_e32 v58, v0
	v_mov_b32_e32 v59, v0
	v_mov_b32_e32 v60, v0
	v_mov_b32_e32 v61, v0
	v_mov_b32_e32 v62, v0
	v_mov_b32_e32 v63, v0
	v_mov_b32_e32 v64, v0
	v_mov_b32_e32 v65, v0
	v_mov_b32_e32 v66, v0
	v_mov_b32_e32 v67, v0
	v_mov_b32_e32 v68, v0
	v_mov_b32_e32 v69, v0
	v_mov_b32_e32 v70, v0
	v_mov_b32_e32 v71, v0
	v_mov_b32_e32 v80, v0
	v_mov_b32_e32 v81, v0
	v_mov_b32_e32 v82, v0
	v_mov_b32_e32 v83, v0
	v_mov_b32_e32 v84, v0
	v_mov_b32_e32 v85, v0
	v_mov_b32_e32 v86, v0
	v_mov_b32_e32 v87, v0
	v_mov_b32_e32 v96, v0
	v_mov_b32_e32 v97, v0
	v_mov_b32_e32 v98, v0
	v_mov_b32_e32 v99, v0
	v_mov_b32_e32 v100, v0
	v_mov_b32_e32 v101, v0
	v_mov_b32_e32 v102, v0
	v_mov_b32_e32 v103, v0
	v_mov_b32_e32 v112, v0
	v_mov_b32_e32 v113, v0
	v_mov_b32_e32 v114, v0
	v_mov_b32_e32 v115, v0
	v_mov_b32_e32 v116, v0
	v_mov_b32_e32 v117, v0
	v_mov_b32_e32 v118, v0
	v_mov_b32_e32 v119, v0
	v_mov_b32_e32 v72, v0
	v_mov_b32_e32 v73, v0
	v_mov_b32_e32 v74, v0
	v_mov_b32_e32 v75, v0
	v_mov_b32_e32 v76, v0
	v_mov_b32_e32 v77, v0
	v_mov_b32_e32 v78, v0
	v_mov_b32_e32 v79, v0
	v_mov_b32_e32 v88, v0
	v_mov_b32_e32 v89, v0
	v_mov_b32_e32 v90, v0
	v_mov_b32_e32 v91, v0
	v_mov_b32_e32 v92, v0
	v_mov_b32_e32 v93, v0
	v_mov_b32_e32 v94, v0
	v_mov_b32_e32 v95, v0
	v_mov_b32_e32 v104, v0
	v_mov_b32_e32 v105, v0
	v_mov_b32_e32 v106, v0
	v_mov_b32_e32 v107, v0
	v_mov_b32_e32 v108, v0
	v_mov_b32_e32 v109, v0
	v_mov_b32_e32 v110, v0
	v_mov_b32_e32 v111, v0
	v_mov_b32_e32 v120, v0
	v_mov_b32_e32 v121, v0
	v_mov_b32_e32 v122, v0
	v_mov_b32_e32 v123, v0
	v_mov_b32_e32 v124, v0
	v_mov_b32_e32 v125, v0
	v_mov_b32_e32 v126, v0
	v_mov_b32_e32 v127, v0
	v_add_u32_e32 v148, 0x80, v128
	v_add_u32_e32 v149, 0x80, v130
	v_readfirstlane_b32 s101, v206
	s_nop 3
	s_lshr_b32 s101, s101, 8
	s_cmp_eq_u32 s101, 0
	s_cbranch_scc0 .Lprio_skip_17
	s_setprio 1

.LBB0_987:
	s_ashr_i32 s19, s18, 31
	s_lshl_b64 s[6:7], s[18:19], 19
	s_add_u32 s20, s34, s6
	s_addc_u32 s21, s35, s7
	s_and_b64 s[6:7], s[4:5], exec
	s_cselect_b32 s19, s21, s29
	s_cselect_b32 s49, s20, s28
	s_ashr_i32 s17, s16, 31
	s_lshl_b64 s[6:7], s[16:17], 19
	s_add_u32 s22, s36, s6
	s_addc_u32 s23, s37, s7
	s_and_b64 s[6:7], s[4:5], exec
	s_cselect_b32 s17, s23, s27
	s_cselect_b32 s50, s22, s26
	s_add_u32 s51, s26, 0x100
	s_addc_u32 s52, s27, 0
	s_add_u32 s6, s28, 0x40080
	v_mov_b32_e32 v0, 0
	s_addc_u32 s7, s29, 0
	s_mov_b32 s53, -2
	v_mov_b32_e32 v1, v0
	v_mov_b32_e32 v2, v0
	v_mov_b32_e32 v3, v0
	v_mov_b32_e32 v4, v0
	v_mov_b32_e32 v5, v0
	v_mov_b32_e32 v6, v0
	v_mov_b32_e32 v7, v0
	v_mov_b32_e32 v16, v0
	v_mov_b32_e32 v17, v0
	v_mov_b32_e32 v18, v0
	v_mov_b32_e32 v19, v0
	v_mov_b32_e32 v20, v0
	v_mov_b32_e32 v21, v0
	v_mov_b32_e32 v22, v0
	v_mov_b32_e32 v23, v0
	v_mov_b32_e32 v32, v0
	v_mov_b32_e32 v33, v0
	v_mov_b32_e32 v34, v0
	v_mov_b32_e32 v35, v0
	v_mov_b32_e32 v36, v0
	v_mov_b32_e32 v37, v0
	v_mov_b32_e32 v38, v0
	v_mov_b32_e32 v39, v0
	v_mov_b32_e32 v48, v0
	v_mov_b32_e32 v49, v0
	v_mov_b32_e32 v50, v0
	v_mov_b32_e32 v51, v0
	v_mov_b32_e32 v52, v0
	v_mov_b32_e32 v53, v0
	v_mov_b32_e32 v54, v0
	v_mov_b32_e32 v55, v0
	v_mov_b32_e32 v8, v0
	v_mov_b32_e32 v9, v0
	v_mov_b32_e32 v10, v0
	v_mov_b32_e32 v11, v0
	v_mov_b32_e32 v12, v0
	v_mov_b32_e32 v13, v0
	v_mov_b32_e32 v14, v0
	v_mov_b32_e32 v15, v0
	v_mov_b32_e32 v24, v0
	v_mov_b32_e32 v25, v0
	v_mov_b32_e32 v26, v0
	v_mov_b32_e32 v27, v0
	v_mov_b32_e32 v28, v0
	v_mov_b32_e32 v29, v0
	v_mov_b32_e32 v30, v0
	v_mov_b32_e32 v31, v0
	v_mov_b32_e32 v40, v0
	v_mov_b32_e32 v41, v0
	v_mov_b32_e32 v42, v0
	v_mov_b32_e32 v43, v0
	v_mov_b32_e32 v44, v0
	v_mov_b32_e32 v45, v0
	v_mov_b32_e32 v46, v0
	v_mov_b32_e32 v47, v0
	v_mov_b32_e32 v56, v0
	v_mov_b32_e32 v57, v0
	v_mov_b32_e32 v58, v0
	v_mov_b32_e32 v59, v0
	v_mov_b32_e32 v60, v0
	v_mov_b32_e32 v61, v0
	v_mov_b32_e32 v62, v0
	v_mov_b32_e32 v63, v0
	v_mov_b32_e32 v64, v0
	v_mov_b32_e32 v65, v0
	v_mov_b32_e32 v66, v0
	v_mov_b32_e32 v67, v0
	v_mov_b32_e32 v68, v0
	v_mov_b32_e32 v69, v0
	v_mov_b32_e32 v70, v0
	v_mov_b32_e32 v71, v0
	v_mov_b32_e32 v80, v0
	v_mov_b32_e32 v81, v0
	v_mov_b32_e32 v82, v0
	v_mov_b32_e32 v83, v0
	v_mov_b32_e32 v84, v0
	v_mov_b32_e32 v85, v0
	v_mov_b32_e32 v86, v0
	v_mov_b32_e32 v87, v0
	v_mov_b32_e32 v96, v0
	v_mov_b32_e32 v97, v0
	v_mov_b32_e32 v98, v0
	v_mov_b32_e32 v99, v0
	v_mov_b32_e32 v100, v0
	v_mov_b32_e32 v101, v0
	v_mov_b32_e32 v102, v0
	v_mov_b32_e32 v103, v0
	v_mov_b32_e32 v112, v0
	v_mov_b32_e32 v113, v0
	v_mov_b32_e32 v114, v0
	v_mov_b32_e32 v115, v0
	v_mov_b32_e32 v116, v0
	v_mov_b32_e32 v117, v0
	v_mov_b32_e32 v118, v0
	v_mov_b32_e32 v119, v0
	v_mov_b32_e32 v72, v0
	v_mov_b32_e32 v73, v0
	v_mov_b32_e32 v74, v0
	v_mov_b32_e32 v75, v0
	v_mov_b32_e32 v76, v0
	v_mov_b32_e32 v77, v0
	v_mov_b32_e32 v78, v0
	v_mov_b32_e32 v79, v0
	v_mov_b32_e32 v88, v0
	v_mov_b32_e32 v89, v0
	v_mov_b32_e32 v90, v0
	v_mov_b32_e32 v91, v0
	v_mov_b32_e32 v92, v0
	v_mov_b32_e32 v93, v0
	v_mov_b32_e32 v94, v0
	v_mov_b32_e32 v95, v0
	v_mov_b32_e32 v104, v0
	v_mov_b32_e32 v105, v0
	v_mov_b32_e32 v106, v0
	v_mov_b32_e32 v107, v0
	v_mov_b32_e32 v108, v0
	v_mov_b32_e32 v109, v0
	v_mov_b32_e32 v110, v0
	v_mov_b32_e32 v111, v0
	v_mov_b32_e32 v120, v0
	v_mov_b32_e32 v121, v0
	v_mov_b32_e32 v122, v0
	v_mov_b32_e32 v123, v0
	v_mov_b32_e32 v124, v0
	v_mov_b32_e32 v125, v0
	v_mov_b32_e32 v126, v0
	v_mov_b32_e32 v127, v0
	v_add_u32_e32 v204, 0x80, v128
	v_add_u32_e32 v205, 0x80, v130
	v_add_u32_e32 v220, 0x80, v132
	v_add_u32_e32 v221, 0x80, v134
	v_readfirstlane_b32 s101, v206
	s_nop 3
	s_lshr_b32 s101, s101, 8
	s_cmp_eq_u32 s101, 0
	s_cbranch_scc0 .Lprio_skip_16
	s_setprio 1

.LBB0_1192:
	s_ashr_i32 s17, s16, 31
	s_lshl_b64 s[18:19], s[16:17], 18
	s_add_u32 s18, s6, s18
	s_addc_u32 s19, s7, s19
	s_and_b64 s[20:21], s[4:5], exec
	s_cselect_b32 s17, s19, s27
	s_cselect_b32 s46, s18, s26
	s_ashr_i32 s15, s14, 31
	s_lshl_b64 s[20:21], s[14:15], 18
	s_add_u32 s20, s34, s20
	s_addc_u32 s21, s35, s21
	s_and_b64 s[28:29], s[4:5], exec
	s_cselect_b32 s15, s21, s25
	s_cselect_b32 s47, s20, s24
	s_add_u32 s48, s24, 0x100
	s_addc_u32 s49, s25, 0
	s_add_u32 s24, s26, 0x20080
	v_mov_b32_e32 v0, 0
	s_addc_u32 s25, s27, 0
	s_mov_b32 s50, -2
	v_mov_b32_e32 v1, v0
	v_mov_b32_e32 v2, v0
	v_mov_b32_e32 v3, v0
	v_mov_b32_e32 v4, v0
	v_mov_b32_e32 v5, v0
	v_mov_b32_e32 v6, v0
	v_mov_b32_e32 v7, v0
	v_mov_b32_e32 v16, v0
	v_mov_b32_e32 v17, v0
	v_mov_b32_e32 v18, v0
	v_mov_b32_e32 v19, v0
	v_mov_b32_e32 v20, v0
	v_mov_b32_e32 v21, v0
	v_mov_b32_e32 v22, v0
	v_mov_b32_e32 v23, v0
	v_mov_b32_e32 v32, v0
	v_mov_b32_e32 v33, v0
	v_mov_b32_e32 v34, v0
	v_mov_b32_e32 v35, v0
	v_mov_b32_e32 v36, v0
	v_mov_b32_e32 v37, v0
	v_mov_b32_e32 v38, v0
	v_mov_b32_e32 v39, v0
	v_mov_b32_e32 v48, v0
	v_mov_b32_e32 v49, v0
	v_mov_b32_e32 v50, v0
	v_mov_b32_e32 v51, v0
	v_mov_b32_e32 v52, v0
	v_mov_b32_e32 v53, v0
	v_mov_b32_e32 v54, v0
	v_mov_b32_e32 v55, v0
	v_mov_b32_e32 v8, v0
	v_mov_b32_e32 v9, v0
	v_mov_b32_e32 v10, v0
	v_mov_b32_e32 v11, v0
	v_mov_b32_e32 v12, v0
	v_mov_b32_e32 v13, v0
	v_mov_b32_e32 v14, v0
	v_mov_b32_e32 v15, v0
	v_mov_b32_e32 v24, v0
	v_mov_b32_e32 v25, v0
	v_mov_b32_e32 v26, v0
	v_mov_b32_e32 v27, v0
	v_mov_b32_e32 v28, v0
	v_mov_b32_e32 v29, v0
	v_mov_b32_e32 v30, v0
	v_mov_b32_e32 v31, v0
	v_mov_b32_e32 v40, v0
	v_mov_b32_e32 v41, v0
	v_mov_b32_e32 v42, v0
	v_mov_b32_e32 v43, v0
	v_mov_b32_e32 v44, v0
	v_mov_b32_e32 v45, v0
	v_mov_b32_e32 v46, v0
	v_mov_b32_e32 v47, v0
	v_mov_b32_e32 v56, v0
	v_mov_b32_e32 v57, v0
	v_mov_b32_e32 v58, v0
	v_mov_b32_e32 v59, v0
	v_mov_b32_e32 v60, v0
	v_mov_b32_e32 v61, v0
	v_mov_b32_e32 v62, v0
	v_mov_b32_e32 v63, v0
	v_mov_b32_e32 v64, v0
	v_mov_b32_e32 v65, v0
	v_mov_b32_e32 v66, v0
	v_mov_b32_e32 v67, v0
	v_mov_b32_e32 v68, v0
	v_mov_b32_e32 v69, v0
	v_mov_b32_e32 v70, v0
	v_mov_b32_e32 v71, v0
	v_mov_b32_e32 v80, v0
	v_mov_b32_e32 v81, v0
	v_mov_b32_e32 v82, v0
	v_mov_b32_e32 v83, v0
	v_mov_b32_e32 v84, v0
	v_mov_b32_e32 v85, v0
	v_mov_b32_e32 v86, v0
	v_mov_b32_e32 v87, v0
	v_mov_b32_e32 v96, v0
	v_mov_b32_e32 v97, v0
	v_mov_b32_e32 v98, v0
	v_mov_b32_e32 v99, v0
	v_mov_b32_e32 v100, v0
	v_mov_b32_e32 v101, v0
	v_mov_b32_e32 v102, v0
	v_mov_b32_e32 v103, v0
	v_mov_b32_e32 v112, v0
	v_mov_b32_e32 v113, v0
	v_mov_b32_e32 v114, v0
	v_mov_b32_e32 v115, v0
	v_mov_b32_e32 v116, v0
	v_mov_b32_e32 v117, v0
	v_mov_b32_e32 v118, v0
	v_mov_b32_e32 v119, v0
	v_mov_b32_e32 v72, v0
	v_mov_b32_e32 v73, v0
	v_mov_b32_e32 v74, v0
	v_mov_b32_e32 v75, v0
	v_mov_b32_e32 v76, v0
	v_mov_b32_e32 v77, v0
	v_mov_b32_e32 v78, v0
	v_mov_b32_e32 v79, v0
	v_mov_b32_e32 v88, v0
	v_mov_b32_e32 v89, v0
	v_mov_b32_e32 v90, v0
	v_mov_b32_e32 v91, v0
	v_mov_b32_e32 v92, v0
	v_mov_b32_e32 v93, v0
	v_mov_b32_e32 v94, v0
	v_mov_b32_e32 v95, v0
	v_mov_b32_e32 v104, v0
	v_mov_b32_e32 v105, v0
	v_mov_b32_e32 v106, v0
	v_mov_b32_e32 v107, v0
	v_mov_b32_e32 v108, v0
	v_mov_b32_e32 v109, v0
	v_mov_b32_e32 v110, v0
	v_mov_b32_e32 v111, v0
	v_mov_b32_e32 v120, v0
	v_mov_b32_e32 v121, v0
	v_mov_b32_e32 v122, v0
	v_mov_b32_e32 v123, v0
	v_mov_b32_e32 v124, v0
	v_mov_b32_e32 v125, v0
	v_mov_b32_e32 v126, v0
	v_mov_b32_e32 v127, v0
	v_add_u32_e32 v216, 0x80, v128
	v_add_u32_e32 v217, 0x80, v130
	v_add_u32_e32 v218, 0x80, v132
	v_add_u32_e32 v219, 0x80, v134
	v_readfirstlane_b32 s101, v206
	s_nop 3
	s_lshr_b32 s101, s101, 8
	s_cmp_eq_u32 s101, 0
	s_cbranch_scc0 .Lprio_skip_15
	s_setprio 1

.LBB0_1364:
	s_ashr_i32 s19, s18, 31
	s_lshl_b64 s[20:21], s[18:19], 19
	s_add_u32 s20, s34, s20
	s_addc_u32 s21, s35, s21
	s_and_b64 s[22:23], s[4:5], exec
	s_cselect_b32 s19, s21, s27
	s_cselect_b32 s49, s20, s26
	s_ashr_i32 s17, s16, 31
	s_lshl_b64 s[22:23], s[16:17], 19
	s_add_u32 s22, s36, s22
	s_addc_u32 s23, s37, s23
	s_and_b64 s[28:29], s[4:5], exec
	s_cselect_b32 s17, s23, s25
	s_cselect_b32 s50, s22, s24
	s_add_u32 s51, s24, 0x100
	s_addc_u32 s52, s25, 0
	s_add_u32 s24, s26, 0x40080
	v_mov_b32_e32 v0, 0
	s_addc_u32 s25, s27, 0
	s_mov_b32 s53, -2
	v_mov_b32_e32 v1, v0
	v_mov_b32_e32 v2, v0
	v_mov_b32_e32 v3, v0
	v_mov_b32_e32 v4, v0
	v_mov_b32_e32 v5, v0
	v_mov_b32_e32 v6, v0
	v_mov_b32_e32 v7, v0
	v_mov_b32_e32 v16, v0
	v_mov_b32_e32 v17, v0
	v_mov_b32_e32 v18, v0
	v_mov_b32_e32 v19, v0
	v_mov_b32_e32 v20, v0
	v_mov_b32_e32 v21, v0
	v_mov_b32_e32 v22, v0
	v_mov_b32_e32 v23, v0
	v_mov_b32_e32 v32, v0
	v_mov_b32_e32 v33, v0
	v_mov_b32_e32 v34, v0
	v_mov_b32_e32 v35, v0
	v_mov_b32_e32 v36, v0
	v_mov_b32_e32 v37, v0
	v_mov_b32_e32 v38, v0
	v_mov_b32_e32 v39, v0
	v_mov_b32_e32 v48, v0
	v_mov_b32_e32 v49, v0
	v_mov_b32_e32 v50, v0
	v_mov_b32_e32 v51, v0
	v_mov_b32_e32 v52, v0
	v_mov_b32_e32 v53, v0
	v_mov_b32_e32 v54, v0
	v_mov_b32_e32 v55, v0
	v_mov_b32_e32 v8, v0
	v_mov_b32_e32 v9, v0
	v_mov_b32_e32 v10, v0
	v_mov_b32_e32 v11, v0
	v_mov_b32_e32 v12, v0
	v_mov_b32_e32 v13, v0
	v_mov_b32_e32 v14, v0
	v_mov_b32_e32 v15, v0
	v_mov_b32_e32 v24, v0
	v_mov_b32_e32 v25, v0
	v_mov_b32_e32 v26, v0
	v_mov_b32_e32 v27, v0
	v_mov_b32_e32 v28, v0
	v_mov_b32_e32 v29, v0
	v_mov_b32_e32 v30, v0
	v_mov_b32_e32 v31, v0
	v_mov_b32_e32 v40, v0
	v_mov_b32_e32 v41, v0
	v_mov_b32_e32 v42, v0
	v_mov_b32_e32 v43, v0
	v_mov_b32_e32 v44, v0
	v_mov_b32_e32 v45, v0
	v_mov_b32_e32 v46, v0
	v_mov_b32_e32 v47, v0
	v_mov_b32_e32 v56, v0
	v_mov_b32_e32 v57, v0
	v_mov_b32_e32 v58, v0
	v_mov_b32_e32 v59, v0
	v_mov_b32_e32 v60, v0
	v_mov_b32_e32 v61, v0
	v_mov_b32_e32 v62, v0
	v_mov_b32_e32 v63, v0
	v_mov_b32_e32 v64, v0
	v_mov_b32_e32 v65, v0
	v_mov_b32_e32 v66, v0
	v_mov_b32_e32 v67, v0
	v_mov_b32_e32 v68, v0
	v_mov_b32_e32 v69, v0
	v_mov_b32_e32 v70, v0
	v_mov_b32_e32 v71, v0
	v_mov_b32_e32 v80, v0
	v_mov_b32_e32 v81, v0
	v_mov_b32_e32 v82, v0
	v_mov_b32_e32 v83, v0
	v_mov_b32_e32 v84, v0
	v_mov_b32_e32 v85, v0
	v_mov_b32_e32 v86, v0
	v_mov_b32_e32 v87, v0
	v_mov_b32_e32 v96, v0
	v_mov_b32_e32 v97, v0
	v_mov_b32_e32 v98, v0
	v_mov_b32_e32 v99, v0
	v_mov_b32_e32 v100, v0
	v_mov_b32_e32 v101, v0
	v_mov_b32_e32 v102, v0
	v_mov_b32_e32 v103, v0
	v_mov_b32_e32 v112, v0
	v_mov_b32_e32 v113, v0
	v_mov_b32_e32 v114, v0
	v_mov_b32_e32 v115, v0
	v_mov_b32_e32 v116, v0
	v_mov_b32_e32 v117, v0
	v_mov_b32_e32 v118, v0
	v_mov_b32_e32 v119, v0
	v_mov_b32_e32 v72, v0
	v_mov_b32_e32 v73, v0
	v_mov_b32_e32 v74, v0
	v_mov_b32_e32 v75, v0
	v_mov_b32_e32 v76, v0
	v_mov_b32_e32 v77, v0
	v_mov_b32_e32 v78, v0
	v_mov_b32_e32 v79, v0
	v_mov_b32_e32 v88, v0
	v_mov_b32_e32 v89, v0
	v_mov_b32_e32 v90, v0
	v_mov_b32_e32 v91, v0
	v_mov_b32_e32 v92, v0
	v_mov_b32_e32 v93, v0
	v_mov_b32_e32 v94, v0
	v_mov_b32_e32 v95, v0
	v_mov_b32_e32 v104, v0
	v_mov_b32_e32 v105, v0
	v_mov_b32_e32 v106, v0
	v_mov_b32_e32 v107, v0
	v_mov_b32_e32 v108, v0
	v_mov_b32_e32 v109, v0
	v_mov_b32_e32 v110, v0
	v_mov_b32_e32 v111, v0
	v_mov_b32_e32 v120, v0
	v_mov_b32_e32 v121, v0
	v_mov_b32_e32 v122, v0
	v_mov_b32_e32 v123, v0
	v_mov_b32_e32 v124, v0
	v_mov_b32_e32 v125, v0
	v_mov_b32_e32 v126, v0
	v_mov_b32_e32 v127, v0
	v_add_u32_e32 v204, 0x80, v128
	v_add_u32_e32 v205, 0x80, v130
	v_add_u32_e32 v220, 0x80, v132
	v_add_u32_e32 v221, 0x80, v134
	v_readfirstlane_b32 s101, v206
	s_nop 3
	s_lshr_b32 s101, s101, 8
	s_cmp_eq_u32 s101, 0
	s_cbranch_scc0 .Lprio_skip_13
	s_setprio 1

.LBB0_1560:
	s_ashr_i32 s29, s28, 31
	s_lshl_b64 s[30:31], s[28:29], 19
	s_add_u32 s30, s12, s30
	s_addc_u32 s31, s13, s31
	s_and_b64 s[34:35], s[6:7], exec
	s_cselect_b32 s3, s31, s39
	s_cselect_b32 s29, s30, s38
	s_ashr_i32 s27, s26, 31
	s_lshl_b64 s[34:35], s[26:27], 19
	s_add_u32 s34, s43, s34
	s_addc_u32 s35, s44, s35
	s_and_b64 s[40:41], s[6:7], exec
	s_cselect_b32 s27, s35, s37
	s_cselect_b32 s58, s34, s36
	s_add_u32 s59, s36, 0x100
	s_addc_u32 s60, s37, 0
	s_add_u32 s36, s38, 0x40080
	v_mov_b32_e32 v0, 0
	s_addc_u32 s37, s39, 0
	s_mov_b32 s61, -2
	v_mov_b32_e32 v1, v0
	v_mov_b32_e32 v2, v0
	v_mov_b32_e32 v3, v0
	v_mov_b32_e32 v4, v0
	v_mov_b32_e32 v5, v0
	v_mov_b32_e32 v6, v0
	v_mov_b32_e32 v7, v0
	v_mov_b32_e32 v16, v0
	v_mov_b32_e32 v17, v0
	v_mov_b32_e32 v18, v0
	v_mov_b32_e32 v19, v0
	v_mov_b32_e32 v20, v0
	v_mov_b32_e32 v21, v0
	v_mov_b32_e32 v22, v0
	v_mov_b32_e32 v23, v0
	v_mov_b32_e32 v32, v0
	v_mov_b32_e32 v33, v0
	v_mov_b32_e32 v34, v0
	v_mov_b32_e32 v35, v0
	v_mov_b32_e32 v36, v0
	v_mov_b32_e32 v37, v0
	v_mov_b32_e32 v38, v0
	v_mov_b32_e32 v39, v0
	v_mov_b32_e32 v48, v0
	v_mov_b32_e32 v49, v0
	v_mov_b32_e32 v50, v0
	v_mov_b32_e32 v51, v0
	v_mov_b32_e32 v52, v0
	v_mov_b32_e32 v53, v0
	v_mov_b32_e32 v54, v0
	v_mov_b32_e32 v55, v0
	v_mov_b32_e32 v8, v0
	v_mov_b32_e32 v9, v0
	v_mov_b32_e32 v10, v0
	v_mov_b32_e32 v11, v0
	v_mov_b32_e32 v12, v0
	v_mov_b32_e32 v13, v0
	v_mov_b32_e32 v14, v0
	v_mov_b32_e32 v15, v0
	v_mov_b32_e32 v24, v0
	v_mov_b32_e32 v25, v0
	v_mov_b32_e32 v26, v0
	v_mov_b32_e32 v27, v0
	v_mov_b32_e32 v28, v0
	v_mov_b32_e32 v29, v0
	v_mov_b32_e32 v30, v0
	v_mov_b32_e32 v31, v0
	v_mov_b32_e32 v40, v0
	v_mov_b32_e32 v41, v0
	v_mov_b32_e32 v42, v0
	v_mov_b32_e32 v43, v0
	v_mov_b32_e32 v44, v0
	v_mov_b32_e32 v45, v0
	v_mov_b32_e32 v46, v0
	v_mov_b32_e32 v47, v0
	v_mov_b32_e32 v56, v0
	v_mov_b32_e32 v57, v0
	v_mov_b32_e32 v58, v0
	v_mov_b32_e32 v59, v0
	v_mov_b32_e32 v60, v0
	v_mov_b32_e32 v61, v0
	v_mov_b32_e32 v62, v0
	v_mov_b32_e32 v63, v0
	v_mov_b32_e32 v64, v0
	v_mov_b32_e32 v65, v0
	v_mov_b32_e32 v66, v0
	v_mov_b32_e32 v67, v0
	v_mov_b32_e32 v68, v0
	v_mov_b32_e32 v69, v0
	v_mov_b32_e32 v70, v0
	v_mov_b32_e32 v71, v0
	v_mov_b32_e32 v80, v0
	v_mov_b32_e32 v81, v0
	v_mov_b32_e32 v82, v0
	v_mov_b32_e32 v83, v0
	v_mov_b32_e32 v84, v0
	v_mov_b32_e32 v85, v0
	v_mov_b32_e32 v86, v0
	v_mov_b32_e32 v87, v0
	v_mov_b32_e32 v96, v0
	v_mov_b32_e32 v97, v0
	v_mov_b32_e32 v98, v0
	v_mov_b32_e32 v99, v0
	v_mov_b32_e32 v100, v0
	v_mov_b32_e32 v101, v0
	v_mov_b32_e32 v102, v0
	v_mov_b32_e32 v103, v0
	v_mov_b32_e32 v112, v0
	v_mov_b32_e32 v113, v0
	v_mov_b32_e32 v114, v0
	v_mov_b32_e32 v115, v0
	v_mov_b32_e32 v116, v0
	v_mov_b32_e32 v117, v0
	v_mov_b32_e32 v118, v0
	v_mov_b32_e32 v119, v0
	v_mov_b32_e32 v72, v0
	v_mov_b32_e32 v73, v0
	v_mov_b32_e32 v74, v0
	v_mov_b32_e32 v75, v0
	v_mov_b32_e32 v76, v0
	v_mov_b32_e32 v77, v0
	v_mov_b32_e32 v78, v0
	v_mov_b32_e32 v79, v0
	v_mov_b32_e32 v88, v0
	v_mov_b32_e32 v89, v0
	v_mov_b32_e32 v90, v0
	v_mov_b32_e32 v91, v0
	v_mov_b32_e32 v92, v0
	v_mov_b32_e32 v93, v0
	v_mov_b32_e32 v94, v0
	v_mov_b32_e32 v95, v0
	v_mov_b32_e32 v104, v0
	v_mov_b32_e32 v105, v0
	v_mov_b32_e32 v106, v0
	v_mov_b32_e32 v107, v0
	v_mov_b32_e32 v108, v0
	v_mov_b32_e32 v109, v0
	v_mov_b32_e32 v110, v0
	v_mov_b32_e32 v111, v0
	v_mov_b32_e32 v120, v0
	v_mov_b32_e32 v121, v0
	v_mov_b32_e32 v122, v0
	v_mov_b32_e32 v123, v0
	v_mov_b32_e32 v124, v0
	v_mov_b32_e32 v125, v0
	v_mov_b32_e32 v126, v0
	v_mov_b32_e32 v127, v0
	v_add_u32_e32 v204, 0x80, v128
	v_add_u32_e32 v205, 0x80, v130
	v_readfirstlane_b32 s101, v206
	s_nop 3
	s_lshr_b32 s101, s101, 8
	s_cmp_eq_u32 s101, 0
	s_cbranch_scc0 .Lprio_skip_11
	s_setprio 1

.LBB0_1645:
	s_ashr_i32 s19, s18, 31
	s_lshl_b64 s[20:21], s[18:19], 19
	s_add_u32 s20, s8, s20
	s_addc_u32 s21, s9, s21
	s_and_b64 s[22:23], s[4:5], exec
	s_cselect_b32 s19, s21, s27
	s_cselect_b32 s50, s20, s26
	s_ashr_i32 s17, s16, 31
	s_lshl_b64 s[22:23], s[16:17], 19
	s_add_u32 s22, s31, s22
	s_addc_u32 s23, s34, s23
	s_and_b64 s[28:29], s[4:5], exec
	s_cselect_b32 s17, s23, s25
	s_cselect_b32 s51, s22, s24
	s_add_u32 s52, s24, 0x100
	s_addc_u32 s53, s25, 0
	s_add_u32 s24, s26, 0x40080
	v_mov_b32_e32 v0, 0
	s_addc_u32 s25, s27, 0
	s_mov_b32 s54, -2
	v_mov_b32_e32 v1, v0
	v_mov_b32_e32 v2, v0
	v_mov_b32_e32 v3, v0
	v_mov_b32_e32 v4, v0
	v_mov_b32_e32 v5, v0
	v_mov_b32_e32 v6, v0
	v_mov_b32_e32 v7, v0
	v_mov_b32_e32 v16, v0
	v_mov_b32_e32 v17, v0
	v_mov_b32_e32 v18, v0
	v_mov_b32_e32 v19, v0
	v_mov_b32_e32 v20, v0
	v_mov_b32_e32 v21, v0
	v_mov_b32_e32 v22, v0
	v_mov_b32_e32 v23, v0
	v_mov_b32_e32 v32, v0
	v_mov_b32_e32 v33, v0
	v_mov_b32_e32 v34, v0
	v_mov_b32_e32 v35, v0
	v_mov_b32_e32 v36, v0
	v_mov_b32_e32 v37, v0
	v_mov_b32_e32 v38, v0
	v_mov_b32_e32 v39, v0
	v_mov_b32_e32 v48, v0
	v_mov_b32_e32 v49, v0
	v_mov_b32_e32 v50, v0
	v_mov_b32_e32 v51, v0
	v_mov_b32_e32 v52, v0
	v_mov_b32_e32 v53, v0
	v_mov_b32_e32 v54, v0
	v_mov_b32_e32 v55, v0
	v_mov_b32_e32 v8, v0
	v_mov_b32_e32 v9, v0
	v_mov_b32_e32 v10, v0
	v_mov_b32_e32 v11, v0
	v_mov_b32_e32 v12, v0
	v_mov_b32_e32 v13, v0
	v_mov_b32_e32 v14, v0
	v_mov_b32_e32 v15, v0
	v_mov_b32_e32 v24, v0
	v_mov_b32_e32 v25, v0
	v_mov_b32_e32 v26, v0
	v_mov_b32_e32 v27, v0
	v_mov_b32_e32 v28, v0
	v_mov_b32_e32 v29, v0
	v_mov_b32_e32 v30, v0
	v_mov_b32_e32 v31, v0
	v_mov_b32_e32 v40, v0
	v_mov_b32_e32 v41, v0
	v_mov_b32_e32 v42, v0
	v_mov_b32_e32 v43, v0
	v_mov_b32_e32 v44, v0
	v_mov_b32_e32 v45, v0
	v_mov_b32_e32 v46, v0
	v_mov_b32_e32 v47, v0
	v_mov_b32_e32 v56, v0
	v_mov_b32_e32 v57, v0
	v_mov_b32_e32 v58, v0
	v_mov_b32_e32 v59, v0
	v_mov_b32_e32 v60, v0
	v_mov_b32_e32 v61, v0
	v_mov_b32_e32 v62, v0
	v_mov_b32_e32 v63, v0
	v_mov_b32_e32 v64, v0
	v_mov_b32_e32 v65, v0
	v_mov_b32_e32 v66, v0
	v_mov_b32_e32 v67, v0
	v_mov_b32_e32 v68, v0
	v_mov_b32_e32 v69, v0
	v_mov_b32_e32 v70, v0
	v_mov_b32_e32 v71, v0
	v_mov_b32_e32 v80, v0
	v_mov_b32_e32 v81, v0
	v_mov_b32_e32 v82, v0
	v_mov_b32_e32 v83, v0
	v_mov_b32_e32 v84, v0
	v_mov_b32_e32 v85, v0
	v_mov_b32_e32 v86, v0
	v_mov_b32_e32 v87, v0
	v_mov_b32_e32 v96, v0
	v_mov_b32_e32 v97, v0
	v_mov_b32_e32 v98, v0
	v_mov_b32_e32 v99, v0
	v_mov_b32_e32 v100, v0
	v_mov_b32_e32 v101, v0
	v_mov_b32_e32 v102, v0
	v_mov_b32_e32 v103, v0
	v_mov_b32_e32 v112, v0
	v_mov_b32_e32 v113, v0
	v_mov_b32_e32 v114, v0
	v_mov_b32_e32 v115, v0
	v_mov_b32_e32 v116, v0
	v_mov_b32_e32 v117, v0
	v_mov_b32_e32 v118, v0
	v_mov_b32_e32 v119, v0
	v_mov_b32_e32 v72, v0
	v_mov_b32_e32 v73, v0
	v_mov_b32_e32 v74, v0
	v_mov_b32_e32 v75, v0
	v_mov_b32_e32 v76, v0
	v_mov_b32_e32 v77, v0
	v_mov_b32_e32 v78, v0
	v_mov_b32_e32 v79, v0
	v_mov_b32_e32 v88, v0
	v_mov_b32_e32 v89, v0
	v_mov_b32_e32 v90, v0
	v_mov_b32_e32 v91, v0
	v_mov_b32_e32 v92, v0
	v_mov_b32_e32 v93, v0
	v_mov_b32_e32 v94, v0
	v_mov_b32_e32 v95, v0
	v_mov_b32_e32 v104, v0
	v_mov_b32_e32 v105, v0
	v_mov_b32_e32 v106, v0
	v_mov_b32_e32 v107, v0
	v_mov_b32_e32 v108, v0
	v_mov_b32_e32 v109, v0
	v_mov_b32_e32 v110, v0
	v_mov_b32_e32 v111, v0
	v_mov_b32_e32 v120, v0
	v_mov_b32_e32 v121, v0
	v_mov_b32_e32 v122, v0
	v_mov_b32_e32 v123, v0
	v_mov_b32_e32 v124, v0
	v_mov_b32_e32 v125, v0
	v_mov_b32_e32 v126, v0
	v_mov_b32_e32 v127, v0
	v_add_u32_e32 v204, 0x80, v128
	v_add_u32_e32 v205, 0x80, v130
	v_add_u32_e32 v220, 0x80, v132
	v_add_u32_e32 v221, 0x80, v134
	v_readfirstlane_b32 s101, v206
	s_nop 3
	s_lshr_b32 s101, s101, 8
	s_cmp_eq_u32 s101, 0
	s_cbranch_scc0 .Lprio_skip_10
	s_setprio 1

.LBB0_3040:
	s_ashr_i32 s29, s28, 31
	s_lshl_b64 s[30:31], s[28:29], 19
	s_add_u32 s30, s8, s30
	s_addc_u32 s31, s9, s31
	s_and_b64 s[34:35], s[6:7], exec
	s_cselect_b32 s3, s31, s39
	s_cselect_b32 s29, s30, s38
	s_ashr_i32 s27, s26, 31
	s_lshl_b64 s[34:35], s[26:27], 19
	s_add_u32 s34, s43, s34
	s_addc_u32 s35, s44, s35
	s_and_b64 s[40:41], s[6:7], exec
	s_cselect_b32 s27, s35, s37
	s_cselect_b32 s58, s34, s36
	s_add_u32 s59, s36, 0x100
	s_addc_u32 s60, s37, 0
	s_add_u32 s36, s38, 0x40080
	v_mov_b32_e32 v0, 0
	s_addc_u32 s37, s39, 0
	s_mov_b32 s61, -2
	v_mov_b32_e32 v1, v0
	v_mov_b32_e32 v2, v0
	v_mov_b32_e32 v3, v0
	v_mov_b32_e32 v4, v0
	v_mov_b32_e32 v5, v0
	v_mov_b32_e32 v6, v0
	v_mov_b32_e32 v7, v0
	v_mov_b32_e32 v16, v0
	v_mov_b32_e32 v17, v0
	v_mov_b32_e32 v18, v0
	v_mov_b32_e32 v19, v0
	v_mov_b32_e32 v20, v0
	v_mov_b32_e32 v21, v0
	v_mov_b32_e32 v22, v0
	v_mov_b32_e32 v23, v0
	v_mov_b32_e32 v32, v0
	v_mov_b32_e32 v33, v0
	v_mov_b32_e32 v34, v0
	v_mov_b32_e32 v35, v0
	v_mov_b32_e32 v36, v0
	v_mov_b32_e32 v37, v0
	v_mov_b32_e32 v38, v0
	v_mov_b32_e32 v39, v0
	v_mov_b32_e32 v48, v0
	v_mov_b32_e32 v49, v0
	v_mov_b32_e32 v50, v0
	v_mov_b32_e32 v51, v0
	v_mov_b32_e32 v52, v0
	v_mov_b32_e32 v53, v0
	v_mov_b32_e32 v54, v0
	v_mov_b32_e32 v55, v0
	v_mov_b32_e32 v8, v0
	v_mov_b32_e32 v9, v0
	v_mov_b32_e32 v10, v0
	v_mov_b32_e32 v11, v0
	v_mov_b32_e32 v12, v0
	v_mov_b32_e32 v13, v0
	v_mov_b32_e32 v14, v0
	v_mov_b32_e32 v15, v0
	v_mov_b32_e32 v24, v0
	v_mov_b32_e32 v25, v0
	v_mov_b32_e32 v26, v0
	v_mov_b32_e32 v27, v0
	v_mov_b32_e32 v28, v0
	v_mov_b32_e32 v29, v0
	v_mov_b32_e32 v30, v0
	v_mov_b32_e32 v31, v0
	v_mov_b32_e32 v40, v0
	v_mov_b32_e32 v41, v0
	v_mov_b32_e32 v42, v0
	v_mov_b32_e32 v43, v0
	v_mov_b32_e32 v44, v0
	v_mov_b32_e32 v45, v0
	v_mov_b32_e32 v46, v0
	v_mov_b32_e32 v47, v0
	v_mov_b32_e32 v56, v0
	v_mov_b32_e32 v57, v0
	v_mov_b32_e32 v58, v0
	v_mov_b32_e32 v59, v0
	v_mov_b32_e32 v60, v0
	v_mov_b32_e32 v61, v0
	v_mov_b32_e32 v62, v0
	v_mov_b32_e32 v63, v0
	v_mov_b32_e32 v64, v0
	v_mov_b32_e32 v65, v0
	v_mov_b32_e32 v66, v0
	v_mov_b32_e32 v67, v0
	v_mov_b32_e32 v68, v0
	v_mov_b32_e32 v69, v0
	v_mov_b32_e32 v70, v0
	v_mov_b32_e32 v71, v0
	v_mov_b32_e32 v80, v0
	v_mov_b32_e32 v81, v0
	v_mov_b32_e32 v82, v0
	v_mov_b32_e32 v83, v0
	v_mov_b32_e32 v84, v0
	v_mov_b32_e32 v85, v0
	v_mov_b32_e32 v86, v0
	v_mov_b32_e32 v87, v0
	v_mov_b32_e32 v96, v0
	v_mov_b32_e32 v97, v0
	v_mov_b32_e32 v98, v0
	v_mov_b32_e32 v99, v0
	v_mov_b32_e32 v100, v0
	v_mov_b32_e32 v101, v0
	v_mov_b32_e32 v102, v0
	v_mov_b32_e32 v103, v0
	v_mov_b32_e32 v112, v0
	v_mov_b32_e32 v113, v0
	v_mov_b32_e32 v114, v0
	v_mov_b32_e32 v115, v0
	v_mov_b32_e32 v116, v0
	v_mov_b32_e32 v117, v0
	v_mov_b32_e32 v118, v0
	v_mov_b32_e32 v119, v0
	v_mov_b32_e32 v72, v0
	v_mov_b32_e32 v73, v0
	v_mov_b32_e32 v74, v0
	v_mov_b32_e32 v75, v0
	v_mov_b32_e32 v76, v0
	v_mov_b32_e32 v77, v0
	v_mov_b32_e32 v78, v0
	v_mov_b32_e32 v79, v0
	v_mov_b32_e32 v88, v0
	v_mov_b32_e32 v89, v0
	v_mov_b32_e32 v90, v0
	v_mov_b32_e32 v91, v0
	v_mov_b32_e32 v92, v0
	v_mov_b32_e32 v93, v0
	v_mov_b32_e32 v94, v0
	v_mov_b32_e32 v95, v0
	v_mov_b32_e32 v104, v0
	v_mov_b32_e32 v105, v0
	v_mov_b32_e32 v106, v0
	v_mov_b32_e32 v107, v0
	v_mov_b32_e32 v108, v0
	v_mov_b32_e32 v109, v0
	v_mov_b32_e32 v110, v0
	v_mov_b32_e32 v111, v0
	v_mov_b32_e32 v120, v0
	v_mov_b32_e32 v121, v0
	v_mov_b32_e32 v122, v0
	v_mov_b32_e32 v123, v0
	v_mov_b32_e32 v124, v0
	v_mov_b32_e32 v125, v0
	v_mov_b32_e32 v126, v0
	v_mov_b32_e32 v127, v0
	v_add_u32_e32 v204, 0x80, v128
	v_add_u32_e32 v205, 0x80, v130
	v_readfirstlane_b32 s101, v206
	s_nop 3
	s_lshr_b32 s101, s101, 8
	s_cmp_eq_u32 s101, 0
	s_cbranch_scc0 .Lprio_skip_0
	s_setprio 1
